# context fourier / hyena items: runs of serialized LDS read->wait->fma steps issued together (same accumulation order)
# speedup vs baseline: 1.0287x; 1.0017x over previous
; DI void fourier_ctx_item(const P& p, int b, int g, int mc, unsigned char* lds) {
;     ...
;   for (int i = tid; i < 256 * 4; i += NT) {
;     int n = i >> 2, mm = i & 3, m = mc * 4 + mm;
;     float re = 0.f, im = 0.f;
;     for (int j = 0; j < 64; ++j) { float2 t = tw64[(m * j) & 63]; float x = u[n * 65 + j]; re += x * t.x; im += x * t.y; }
;     ab[n * 4 + mm] = make_float2(re, im);
;   }
.LBB0_345:
	v_lshrrev_b32_e32 v68, 2, v67
	v_mul_lo_u32 v68, v68, s17
	v_add_u32_e32 v84, 0, v68
	v_mov_b32_e32 v78, s13
	ds_read2_b32 v[68:69], v84 offset1:1
	ds_read2_b32 v[70:71], v84 offset0:2 offset1:3
	ds_read2_b32 v[72:73], v84 offset0:4 offset1:5
	ds_read2_b32 v[74:75], v84 offset0:6 offset1:7
	ds_read2_b32 v[76:77], v84 offset0:8 offset1:9
	ds_read_b64 v[78:79], v78
	ds_read_b64 v[80:81], v3
	v_cmp_lt_i32_e64 s[0:1], s16, v67
	s_or_b64 s[6:7], s[0:1], s[6:7]
	s_waitcnt lgkmcnt(1)
	v_pk_fma_f32 v[78:79], v[78:79], v[68:69], 0 op_sel_hi:[1,0,0]
	s_waitcnt lgkmcnt(0)
	v_pk_fma_f32 v[68:69], v[80:81], v[68:69], v[78:79] op_sel:[0,1,0]
	ds_read_b64 v[78:79], v4
	s_waitcnt lgkmcnt(0)
	v_pk_fma_f32 v[68:69], v[78:79], v[70:71], v[68:69] op_sel_hi:[1,0,1]
	ds_read_b64 v[78:79], v5
	s_waitcnt lgkmcnt(0)
	v_pk_fma_f32 v[68:69], v[78:79], v[70:71], v[68:69] op_sel:[0,1,0]
	ds_read_b64 v[130:131], v6
	ds_read_b64 v[132:133], v7
	ds_read_b64 v[134:135], v8
	ds_read_b64 v[136:137], v9
	ds_read_b64 v[70:71], v10
	s_waitcnt lgkmcnt(4)
	v_pk_fma_f32 v[68:69], v[130:131], v[72:73], v[68:69] op_sel_hi:[1,0,1]
	s_waitcnt lgkmcnt(3)
	v_pk_fma_f32 v[68:69], v[132:133], v[72:73], v[68:69] op_sel:[0,1,0]
	s_waitcnt lgkmcnt(2)
	v_pk_fma_f32 v[68:69], v[134:135], v[74:75], v[68:69] op_sel_hi:[1,0,1]
	s_waitcnt lgkmcnt(1)
	v_pk_fma_f32 v[68:69], v[136:137], v[74:75], v[68:69] op_sel:[0,1,0]
	s_waitcnt lgkmcnt(0)
	v_pk_fma_f32 v[68:69], v[70:71], v[76:77], v[68:69] op_sel_hi:[1,0,1]
	ds_read_b64 v[70:71], v11
	ds_read2_b32 v[72:73], v84 offset0:10 offset1:11
	ds_read2_b32 v[74:75], v84 offset0:12 offset1:13
	ds_read2_b32 v[78:79], v84 offset0:14 offset1:15
	ds_read2_b32 v[80:81], v84 offset0:16 offset1:17
	ds_read2_b32 v[82:83], v84 offset0:18 offset1:19
	s_waitcnt lgkmcnt(5)
	v_pk_fma_f32 v[68:69], v[70:71], v[76:77], v[68:69] op_sel:[0,1,0]
	ds_read_b64 v[130:131], v12
	ds_read_b64 v[132:133], v13
	ds_read_b64 v[134:135], v14
	ds_read_b64 v[136:137], v15
	ds_read_b64 v[138:139], v16
	ds_read_b64 v[140:141], v17
	ds_read_b64 v[142:143], v66
	ds_read_b64 v[144:145], v18
	ds_read_b64 v[146:147], v19
	ds_read_b64 v[70:71], v20
	s_waitcnt lgkmcnt(9)
	v_pk_fma_f32 v[68:69], v[130:131], v[72:73], v[68:69] op_sel_hi:[1,0,1]
	s_waitcnt lgkmcnt(8)
	v_pk_fma_f32 v[68:69], v[132:133], v[72:73], v[68:69] op_sel:[0,1,0]
	s_waitcnt lgkmcnt(7)
	v_pk_fma_f32 v[68:69], v[134:135], v[74:75], v[68:69] op_sel_hi:[1,0,1]
	s_waitcnt lgkmcnt(6)
	v_pk_fma_f32 v[68:69], v[136:137], v[74:75], v[68:69] op_sel:[0,1,0]
	s_waitcnt lgkmcnt(5)
	v_pk_fma_f32 v[68:69], v[138:139], v[78:79], v[68:69] op_sel_hi:[1,0,1]
	s_waitcnt lgkmcnt(4)
	v_pk_fma_f32 v[68:69], v[140:141], v[78:79], v[68:69] op_sel:[0,1,0]
	s_waitcnt lgkmcnt(3)
	v_pk_fma_f32 v[68:69], v[142:143], v[80:81], v[68:69] op_sel_hi:[1,0,1]
	s_waitcnt lgkmcnt(2)
	v_pk_fma_f32 v[68:69], v[144:145], v[80:81], v[68:69] op_sel:[0,1,0]
	s_waitcnt lgkmcnt(1)
	v_pk_fma_f32 v[68:69], v[146:147], v[82:83], v[68:69] op_sel_hi:[1,0,1]
	s_waitcnt lgkmcnt(0)
	v_pk_fma_f32 v[68:69], v[70:71], v[82:83], v[68:69] op_sel:[0,1,0]
	ds_read2_b32 v[70:71], v84 offset0:20 offset1:21
	ds_read_b64 v[72:73], v21
	ds_read2_b32 v[74:75], v84 offset0:22 offset1:23
	ds_read2_b32 v[76:77], v84 offset0:24 offset1:25
	ds_read2_b32 v[78:79], v84 offset0:26 offset1:27
	ds_read2_b32 v[80:81], v84 offset0:28 offset1:29
	ds_read2_b32 v[82:83], v84 offset0:30 offset1:31
	s_waitcnt lgkmcnt(5)
	v_pk_fma_f32 v[68:69], v[72:73], v[70:71], v[68:69] op_sel_hi:[1,0,1]
	ds_read_b64 v[72:73], v22
	s_waitcnt lgkmcnt(0)
	v_pk_fma_f32 v[68:69], v[72:73], v[70:71], v[68:69] op_sel:[0,1,0]
	ds_read_b64 v[130:131], v23
	ds_read_b64 v[132:133], v24
	ds_read_b64 v[134:135], v25
	ds_read_b64 v[136:137], v26
	ds_read_b64 v[138:139], v27
	ds_read_b64 v[140:141], v28
	ds_read_b64 v[142:143], v29
	ds_read_b64 v[144:145], v30
	ds_read_b64 v[70:71], v31
	s_waitcnt lgkmcnt(8)
	v_pk_fma_f32 v[68:69], v[130:131], v[74:75], v[68:69] op_sel_hi:[1,0,1]
	s_waitcnt lgkmcnt(7)
	v_pk_fma_f32 v[68:69], v[132:133], v[74:75], v[68:69] op_sel:[0,1,0]
	s_waitcnt lgkmcnt(6)
	v_pk_fma_f32 v[68:69], v[134:135], v[76:77], v[68:69] op_sel_hi:[1,0,1]
	s_waitcnt lgkmcnt(5)
	v_pk_fma_f32 v[68:69], v[136:137], v[76:77], v[68:69] op_sel:[0,1,0]
	s_waitcnt lgkmcnt(4)
	v_pk_fma_f32 v[68:69], v[138:139], v[78:79], v[68:69] op_sel_hi:[1,0,1]
	s_waitcnt lgkmcnt(3)
	v_pk_fma_f32 v[68:69], v[140:141], v[78:79], v[68:69] op_sel:[0,1,0]
	s_waitcnt lgkmcnt(2)
	v_pk_fma_f32 v[68:69], v[142:143], v[80:81], v[68:69] op_sel_hi:[1,0,1]
	s_waitcnt lgkmcnt(1)
	v_pk_fma_f32 v[68:69], v[144:145], v[80:81], v[68:69] op_sel:[0,1,0]
	s_waitcnt lgkmcnt(0)
	v_pk_fma_f32 v[68:69], v[70:71], v[82:83], v[68:69] op_sel_hi:[1,0,1]
	ds_read_b64 v[70:71], v32
	ds_read2_b32 v[72:73], v84 offset0:32 offset1:33
	ds_read2_b32 v[74:75], v84 offset0:34 offset1:35
	ds_read2_b32 v[76:77], v84 offset0:36 offset1:37
	ds_read2_b32 v[78:79], v84 offset0:38 offset1:39
	ds_read2_b32 v[80:81], v84 offset0:40 offset1:41
	s_waitcnt lgkmcnt(5)
; DI void fourier_ctx_item(const P& p, int b, int g, int mc, unsigned char* lds) {
;     ...
;   for (int i = tid; i < 256 * 4; i += NT) {
;     int n = i >> 2, mm = i & 3, m = mc * 4 + mm;
;     float re = 0.f, im = 0.f;
;     for (int j = 0; j < 64; ++j) { float2 t = tw64[(m * j) & 63]; float x = u[n * 65 + j]; re += x * t.x; im += x * t.y; }
;     ab[n * 4 + mm] = make_float2(re, im);
;   }
	v_pk_fma_f32 v[68:69], v[70:71], v[82:83], v[68:69] op_sel:[0,1,0]
	ds_read_b64 v[130:131], v33
	ds_read_b64 v[132:133], v34
	ds_read_b64 v[134:135], v35
	ds_read_b64 v[136:137], v36
	ds_read_b64 v[138:139], v37
	ds_read_b64 v[140:141], v38
	ds_read_b64 v[142:143], v39
	ds_read_b64 v[144:145], v40
	ds_read_b64 v[146:147], v41
	ds_read_b64 v[70:71], v42
	s_waitcnt lgkmcnt(9)
	v_pk_fma_f32 v[68:69], v[130:131], v[72:73], v[68:69] op_sel_hi:[1,0,1]
	s_waitcnt lgkmcnt(8)
	v_pk_fma_f32 v[68:69], v[132:133], v[72:73], v[68:69] op_sel:[0,1,0]
	s_waitcnt lgkmcnt(7)
	v_pk_fma_f32 v[68:69], v[134:135], v[74:75], v[68:69] op_sel_hi:[1,0,1]
	s_waitcnt lgkmcnt(6)
	v_pk_fma_f32 v[68:69], v[136:137], v[74:75], v[68:69] op_sel:[0,1,0]
	s_waitcnt lgkmcnt(5)
	v_pk_fma_f32 v[68:69], v[138:139], v[76:77], v[68:69] op_sel_hi:[1,0,1]
	s_waitcnt lgkmcnt(4)
	v_pk_fma_f32 v[68:69], v[140:141], v[76:77], v[68:69] op_sel:[0,1,0]
	s_waitcnt lgkmcnt(3)
	v_pk_fma_f32 v[68:69], v[142:143], v[78:79], v[68:69] op_sel_hi:[1,0,1]
	s_waitcnt lgkmcnt(2)
	v_pk_fma_f32 v[68:69], v[144:145], v[78:79], v[68:69] op_sel:[0,1,0]
	s_waitcnt lgkmcnt(1)
	v_pk_fma_f32 v[68:69], v[146:147], v[80:81], v[68:69] op_sel_hi:[1,0,1]
	s_waitcnt lgkmcnt(0)
	v_pk_fma_f32 v[68:69], v[70:71], v[80:81], v[68:69] op_sel:[0,1,0]
	ds_read2_b32 v[70:71], v84 offset0:42 offset1:43
	ds_read_b64 v[72:73], v43
	ds_read2_b32 v[74:75], v84 offset0:44 offset1:45
	ds_read2_b32 v[76:77], v84 offset0:46 offset1:47
	ds_read2_b32 v[78:79], v84 offset0:48 offset1:49
	ds_read2_b32 v[80:81], v84 offset0:50 offset1:51
	ds_read2_b32 v[82:83], v84 offset0:52 offset1:53
	s_waitcnt lgkmcnt(5)
	v_pk_fma_f32 v[68:69], v[72:73], v[70:71], v[68:69] op_sel_hi:[1,0,1]
	ds_read_b64 v[72:73], v44
	s_waitcnt lgkmcnt(0)
	v_pk_fma_f32 v[68:69], v[72:73], v[70:71], v[68:69] op_sel:[0,1,0]
	ds_read_b64 v[130:131], v45
	ds_read_b64 v[132:133], v46
	ds_read_b64 v[134:135], v47
	ds_read_b64 v[136:137], v48
	ds_read_b64 v[138:139], v49
	ds_read_b64 v[140:141], v50
	ds_read_b64 v[142:143], v51
	ds_read_b64 v[144:145], v52
	ds_read_b64 v[70:71], v53
	s_waitcnt lgkmcnt(8)
	v_pk_fma_f32 v[68:69], v[130:131], v[74:75], v[68:69] op_sel_hi:[1,0,1]
	s_waitcnt lgkmcnt(7)
	v_pk_fma_f32 v[68:69], v[132:133], v[74:75], v[68:69] op_sel:[0,1,0]
	s_waitcnt lgkmcnt(6)
	v_pk_fma_f32 v[68:69], v[134:135], v[76:77], v[68:69] op_sel_hi:[1,0,1]
	s_waitcnt lgkmcnt(5)
	v_pk_fma_f32 v[68:69], v[136:137], v[76:77], v[68:69] op_sel:[0,1,0]
	s_waitcnt lgkmcnt(4)
	v_pk_fma_f32 v[68:69], v[138:139], v[78:79], v[68:69] op_sel_hi:[1,0,1]
	s_waitcnt lgkmcnt(3)
	v_pk_fma_f32 v[68:69], v[140:141], v[78:79], v[68:69] op_sel:[0,1,0]
	s_waitcnt lgkmcnt(2)
	v_pk_fma_f32 v[68:69], v[142:143], v[80:81], v[68:69] op_sel_hi:[1,0,1]
	s_waitcnt lgkmcnt(1)
	v_pk_fma_f32 v[68:69], v[144:145], v[80:81], v[68:69] op_sel:[0,1,0]
	s_waitcnt lgkmcnt(0)
	v_pk_fma_f32 v[68:69], v[70:71], v[82:83], v[68:69] op_sel_hi:[1,0,1]
	ds_read_b64 v[70:71], v54
	ds_read2_b32 v[72:73], v84 offset0:54 offset1:55
	ds_read2_b32 v[74:75], v84 offset0:56 offset1:57
	ds_read2_b32 v[76:77], v84 offset0:58 offset1:59
	ds_read2_b32 v[78:79], v84 offset0:60 offset1:61
	ds_read2_b32 v[80:81], v84 offset0:62 offset1:63
	s_waitcnt lgkmcnt(5)
	v_pk_fma_f32 v[68:69], v[70:71], v[82:83], v[68:69] op_sel:[0,1,0]
	ds_read_b64 v[130:131], v55
	ds_read_b64 v[132:133], v56
	ds_read_b64 v[134:135], v57
	ds_read_b64 v[136:137], v58
	ds_read_b64 v[138:139], v59
	ds_read_b64 v[140:141], v60
	ds_read_b64 v[142:143], v61
	ds_read_b64 v[144:145], v62
	ds_read_b64 v[146:147], v63
	ds_read_b64 v[70:71], v64
	s_waitcnt lgkmcnt(9)
	v_pk_fma_f32 v[68:69], v[130:131], v[72:73], v[68:69] op_sel_hi:[1,0,1]
	s_waitcnt lgkmcnt(8)
	v_pk_fma_f32 v[68:69], v[132:133], v[72:73], v[68:69] op_sel:[0,1,0]
	s_waitcnt lgkmcnt(7)
	v_pk_fma_f32 v[68:69], v[134:135], v[74:75], v[68:69] op_sel_hi:[1,0,1]
	s_waitcnt lgkmcnt(6)
	v_pk_fma_f32 v[68:69], v[136:137], v[74:75], v[68:69] op_sel:[0,1,0]
	s_waitcnt lgkmcnt(5)
	v_pk_fma_f32 v[68:69], v[138:139], v[76:77], v[68:69] op_sel_hi:[1,0,1]
	s_waitcnt lgkmcnt(4)
	v_pk_fma_f32 v[68:69], v[140:141], v[76:77], v[68:69] op_sel:[0,1,0]
	s_waitcnt lgkmcnt(3)
	v_pk_fma_f32 v[68:69], v[142:143], v[78:79], v[68:69] op_sel_hi:[1,0,1]
	s_waitcnt lgkmcnt(2)
	v_pk_fma_f32 v[68:69], v[144:145], v[78:79], v[68:69] op_sel:[0,1,0]
	s_waitcnt lgkmcnt(1)
	v_pk_fma_f32 v[68:69], v[146:147], v[80:81], v[68:69] op_sel_hi:[1,0,1]
	s_waitcnt lgkmcnt(0)
	v_pk_fma_f32 v[68:69], v[70:71], v[80:81], v[68:69] op_sel:[0,1,0]
	ds_write_b64 v65, v[68:69]
	v_add_u32_e32 v68, 0x200, v67
	v_add_u32_e32 v65, 0x1000, v65
	v_mov_b32_e32 v67, v68
	s_andn2_b64 exec, exec, s[6:7]
	s_cbranch_execnz .LBB0_345

; DI u16 f2bf(float a) { return (u16)(pack2(a, 0.f) & 0xffffu); }
; DI void fourier_ctx_item(const P& p, int b, int g, int mc, unsigned char* lds) {
;     ...
;   for (int i = tid; i < 256 * 4; i += NT) {
;     int k = i >> 2, mm = i & 3;
;     float y = 0.f;
;     for (int n = 0; n < 256; ++n) { float2 t = tw256[(k * n) & 255]; float2 z = ab[n * 4 + mm]; y += z.x * t.x - z.y * t.y; }
;     FM[(size_t)(T + b * LC + k) * 256 + g * 64 + mc * 4 + mm] = f2bf(y * (1.f / 128.f));
;   }
.LBB0_349:
	s_add_i32 s10, 0, 0x18600
	v_add_u32_e32 v20, s7, v1
	v_add_u32_e32 v210, 0x12400, v20
	v_and_b32_e32 v130, 0xf8, v13
	v_add_u32_e32 v131, v3, v13
	v_add_u32_e32 v132, v7, v13
	v_add_u32_e32 v133, v8, v13
	v_add_u32_e32 v134, v9, v13
	v_add_u32_e32 v135, v10, v13
	v_add_u32_e32 v136, v11, v13
	v_add_u32_e32 v137, v12, v13
	v_and_b32_e32 v131, 0xff, v131
	v_and_b32_e32 v132, 0xfe, v132
	v_and_b32_e32 v133, 0xff, v133
	v_and_b32_e32 v134, 0xfc, v134
	v_and_b32_e32 v135, 0xff, v135
	v_and_b32_e32 v136, 0xfe, v136
	v_and_b32_e32 v137, 0xff, v137
	v_lshl_add_u32 v130, v130, 3, s10
	v_lshl_add_u32 v131, v131, 3, s10
	v_lshl_add_u32 v132, v132, 3, s10
	v_lshl_add_u32 v133, v133, 3, s10
	v_lshl_add_u32 v134, v134, 3, s10
	v_lshl_add_u32 v135, v135, 3, s10
	v_lshl_add_u32 v136, v136, 3, s10
	v_lshl_add_u32 v137, v137, 3, s10
	ds_read_b64 v[138:139], v130
	ds_read_b64 v[154:155], v210
	ds_read_b64 v[140:141], v131
	ds_read_b64 v[156:157], v210 offset:32
	ds_read_b64 v[142:143], v132
	ds_read_b64 v[158:159], v210 offset:64
	ds_read_b64 v[144:145], v133
	ds_read_b64 v[160:161], v210 offset:96
	ds_read_b64 v[146:147], v134
	ds_read_b64 v[180:181], v210 offset:128
	ds_read_b64 v[148:149], v135
	ds_read_b64 v[182:183], v210 offset:160
	ds_read_b64 v[150:151], v136
	ds_read_b64 v[184:185], v210 offset:192
	ds_read_b64 v[152:153], v137
	ds_read_b64 v[186:187], v210 offset:224
	s_addk_i32 s7, 0x100
	s_cmp_eq_u32 s7, 0
	v_add_u32_e32 v13, v13, v6
	s_waitcnt lgkmcnt(14)
	v_pk_mul_f32 v[138:139], v[138:139], v[154:155]
	s_nop 0
	v_sub_f32_e32 v138, v138, v139
	v_add_f32_e32 v18, v14, v138
	s_waitcnt lgkmcnt(12)
	v_pk_mul_f32 v[140:141], v[140:141], v[156:157]
	s_nop 0
	v_sub_f32_e32 v140, v140, v141
	v_add_f32_e32 v18, v18, v140
	s_waitcnt lgkmcnt(10)
	v_pk_mul_f32 v[142:143], v[142:143], v[158:159]
	s_nop 0
	v_sub_f32_e32 v142, v142, v143
	v_add_f32_e32 v18, v18, v142
	s_waitcnt lgkmcnt(8)
	v_pk_mul_f32 v[144:145], v[144:145], v[160:161]
	s_nop 0
	v_sub_f32_e32 v144, v144, v145
	v_add_f32_e32 v18, v18, v144
	s_waitcnt lgkmcnt(6)
	v_pk_mul_f32 v[146:147], v[146:147], v[180:181]
	s_nop 0
	v_sub_f32_e32 v146, v146, v147
	v_add_f32_e32 v18, v18, v146
	s_waitcnt lgkmcnt(4)
	v_pk_mul_f32 v[148:149], v[148:149], v[182:183]
	s_nop 0
	v_sub_f32_e32 v148, v148, v149
	v_add_f32_e32 v18, v18, v148
	s_waitcnt lgkmcnt(2)
	v_pk_mul_f32 v[150:151], v[150:151], v[184:185]
	s_nop 0
	v_sub_f32_e32 v150, v150, v151
	v_add_f32_e32 v18, v18, v150
	s_waitcnt lgkmcnt(0)
	v_pk_mul_f32 v[152:153], v[152:153], v[186:187]
	s_nop 0
	v_sub_f32_e32 v152, v152, v153
	v_add_f32_e32 v14, v18, v152
	s_cbranch_scc0 .LBB0_349
	v_mul_f32_e32 v6, 0x3c000000, v14
	v_cvt_pk_bf16_f32 v8, v6, s0
	v_add_u32_e32 v6, s6, v3
	v_ashrrev_i32_e32 v7, 31, v6
	s_movk_i32 s7, 0x1ff
	v_lshlrev_b64 v[6:7], 9, v[6:7]
	v_add_u32_e32 v3, 0x200, v2
	v_cmp_lt_i32_e32 vcc, s7, v2
	v_lshl_add_u64 v[6:7], v[4:5], 0, v[6:7]
	s_or_b64 s[4:5], vcc, s[4:5]
	v_mov_b32_e32 v2, v3
	global_store_short v[6:7], v8, off
	s_andn2_b64 exec, exec, s[4:5]
	s_cbranch_execnz .LBB0_348
